# RMSNorm row loops of P0/P5/P8 rewritten by hand (norm weight in registers, rows double-buffered, counted vmcnt) and P0 transposes with two items in flight
# speedup vs baseline: 1.0117x; 1.0045x over previous
.LBB0_17:
	s_add_u32 s70, s28, 0x500000
	s_addc_u32 s71, s29, 0
	s_add_u32 s68, s28, 0x700000
	s_addc_u32 s69, s29, 0
	s_add_u32 s72, s28, 0x800000
	s_addc_u32 s73, s29, 0
	s_add_u32 s66, s28, 0x1800000
	s_addc_u32 s67, s29, 0
	s_add_u32 s64, s28, 0x2000000
	s_addc_u32 s65, s29, 0
	s_load_dwordx16 s[12:27], s[0:1], 0x40
	s_add_u32 s0, s28, 0x4c00000
	s_addc_u32 s1, s29, 0
	v_writelane_b32 v254, s0, 3
	v_and_b32_e32 v204, 63, v205
	s_nop 0
	v_writelane_b32 v254, s1, 4
	v_writelane_b32 v254, s33, 5
	s_lshr_b32 s33, s33, 6
	s_cmp_lt_i32 s30, 1
	s_cselect_b64 s[0:1], -1, 0
	s_cmp_gt_i32 s31, 0
	s_cselect_b64 s[4:5], -1, 0
	s_and_b64 s[74:75], s[0:1], s[4:5]
	s_andn2_b64 vcc, exec, s[74:75]
	s_cbranch_vccnz .LBB0_143
	s_lshl_b32 s0, s2, 3
	s_add_i32 s4, s33, s0
	s_lshl_b32 s6, s34, 3
	s_cmpk_gt_i32 s4, 0x5bbf
	s_cbranch_scc1 .LBB0_91
	s_waitcnt lgkmcnt(0)
	v_and_b32_e32 v0, 31, v204
	v_lshrrev_b32_e32 v1, 5, v204
	v_and_b32_e32 v2, 7, v204
	v_lshrrev_b32_e32 v3, 3, v204
	s_lshl_b32 s0, s33, 14
	v_mul_u32_u24_e32 v4, 33, v1
	v_add_u32_e32 v4, v4, v0
	v_lshl_add_u32 v4, v4, 2, s0
	v_mul_u32_u24_e32 v5, 0x108, v2
	v_add_u32_e32 v5, v5, v3
	v_lshl_add_u32 v5, v5, 2, s0
	v_lshlrev_b32_e32 v9, 5, v2
	s_mov_b32 s7, s4
	s_mov_b32 s100, 0
	s_mov_b32 s85, 0
	s_mov_b32 s84, 0
	s_mov_b32 s101, 0
	s_branch .Lp0t_loadA
.Lp0t_stageA:
	s_lshl_b32 s1, s84, 1
	s_add_u32 s1, s1, s100
	s_cmp_eq_u32 s1, 3
	s_cbranch_scc1 .Lp0tA_w36
	s_cmp_eq_u32 s1, 2
	s_cbranch_scc1 .Lp0tA_w32
	s_cmp_eq_u32 s1, 1
	s_cbranch_scc1 .Lp0tA_w4
	s_waitcnt vmcnt(0)
	s_branch .Lp0tA_go
.Lp0tA_w36:
	s_waitcnt vmcnt(36)
	s_branch .Lp0tA_go
.Lp0tA_w32:
	s_waitcnt vmcnt(32)
	s_branch .Lp0tA_go
.Lp0tA_w4:
	s_waitcnt vmcnt(4)
.Lp0tA_go:
	ds_write_b32 v4, v32
	ds_write_b32 v4, v33 offset:264
	ds_write_b32 v4, v34 offset:528
	ds_write_b32 v4, v35 offset:792
	ds_write_b32 v4, v36 offset:1056
	ds_write_b32 v4, v37 offset:1320
	ds_write_b32 v4, v38 offset:1584
	ds_write_b32 v4, v39 offset:1848
	ds_write_b32 v4, v40 offset:2112
	ds_write_b32 v4, v41 offset:2376
	ds_write_b32 v4, v42 offset:2640
	ds_write_b32 v4, v43 offset:2904
	ds_write_b32 v4, v44 offset:3168
	ds_write_b32 v4, v45 offset:3432
	ds_write_b32 v4, v46 offset:3696
	ds_write_b32 v4, v47 offset:3960
	ds_write_b32 v4, v48 offset:4224
	ds_write_b32 v4, v49 offset:4488
	ds_write_b32 v4, v50 offset:4752
	ds_write_b32 v4, v51 offset:5016
	ds_write_b32 v4, v52 offset:5280
	ds_write_b32 v4, v53 offset:5544
	ds_write_b32 v4, v54 offset:5808
	ds_write_b32 v4, v55 offset:6072
	ds_write_b32 v4, v56 offset:6336
	ds_write_b32 v4, v57 offset:6600
	ds_write_b32 v4, v58 offset:6864
	ds_write_b32 v4, v59 offset:7128
	ds_write_b32 v4, v60 offset:7392
	ds_write_b32 v4, v61 offset:7656
	ds_write_b32 v4, v62 offset:7920
	ds_write_b32 v4, v63 offset:8184
	s_waitcnt lgkmcnt(0)
	ds_read2_b32 v[64:65], v5 offset0:0 offset1:33
	ds_read2_b32 v[66:67], v5 offset0:66 offset1:99
	ds_read2_b32 v[68:69], v5 offset0:132 offset1:165
	ds_read2_b32 v[70:71], v5 offset0:198 offset1:231
	ds_read2_b32 v[72:73], v5 offset0:8 offset1:41
	ds_read2_b32 v[74:75], v5 offset0:74 offset1:107
	ds_read2_b32 v[76:77], v5 offset0:140 offset1:173
	ds_read2_b32 v[78:79], v5 offset0:206 offset1:239
	ds_read2_b32 v[80:81], v5 offset0:16 offset1:49
	ds_read2_b32 v[82:83], v5 offset0:82 offset1:115
	ds_read2_b32 v[84:85], v5 offset0:148 offset1:181
	ds_read2_b32 v[86:87], v5 offset0:214 offset1:247
	ds_read2_b32 v[88:89], v5 offset0:24 offset1:57
	ds_read2_b32 v[90:91], v5 offset0:90 offset1:123
	ds_read2_b32 v[92:93], v5 offset0:156 offset1:189
	ds_read2_b32 v[94:95], v5 offset0:222 offset1:255
	s_waitcnt lgkmcnt(12)
	s_cmp_eq_u32 s91, 0
	s_cbranch_scc1 .Lp0tA_ng0
	v_mul_f32_e32 v64, v64, v10
	v_mul_f32_e32 v65, v65, v11
	v_mul_f32_e32 v66, v66, v12
	v_mul_f32_e32 v67, v67, v13
	v_mul_f32_e32 v68, v68, v14
	v_mul_f32_e32 v69, v69, v15
	v_mul_f32_e32 v70, v70, v16
	v_mul_f32_e32 v71, v71, v17
.Lp0tA_ng0:
	v_cvt_pk_bf16_f32 v96, v64, v65
	v_cvt_pk_bf16_f32 v97, v66, v67
	v_cvt_pk_bf16_f32 v98, v68, v69
	v_cvt_pk_bf16_f32 v99, v70, v71
	global_store_dwordx4 v7, v[96:99], s[88:89]
	s_add_u32 s88, s88, s90
	s_addc_u32 s89, s89, 0
	s_waitcnt lgkmcnt(8)
	s_cmp_eq_u32 s91, 0
	s_cbranch_scc1 .Lp0tA_ng1
	v_mul_f32_e32 v72, v72, v10
	v_mul_f32_e32 v73, v73, v11
	v_mul_f32_e32 v74, v74, v12
	v_mul_f32_e32 v75, v75, v13
	v_mul_f32_e32 v76, v76, v14
	v_mul_f32_e32 v77, v77, v15
	v_mul_f32_e32 v78, v78, v16
	v_mul_f32_e32 v79, v79, v17
.Lp0tA_ng1:
	v_cvt_pk_bf16_f32 v100, v72, v73
	v_cvt_pk_bf16_f32 v101, v74, v75
	v_cvt_pk_bf16_f32 v102, v76, v77
	v_cvt_pk_bf16_f32 v103, v78, v79
	global_store_dwordx4 v7, v[100:103], s[88:89]
	s_add_u32 s88, s88, s90
	s_addc_u32 s89, s89, 0
	s_waitcnt lgkmcnt(4)
	s_cmp_eq_u32 s91, 0
	s_cbranch_scc1 .Lp0tA_ng2
	v_mul_f32_e32 v80, v80, v10
	v_mul_f32_e32 v81, v81, v11
	v_mul_f32_e32 v82, v82, v12
	v_mul_f32_e32 v83, v83, v13
	v_mul_f32_e32 v84, v84, v14
	v_mul_f32_e32 v85, v85, v15
	v_mul_f32_e32 v86, v86, v16
	v_mul_f32_e32 v87, v87, v17
.Lp0tA_ng2:
	v_cvt_pk_bf16_f32 v96, v80, v81
	v_cvt_pk_bf16_f32 v97, v82, v83
	v_cvt_pk_bf16_f32 v98, v84, v85
	v_cvt_pk_bf16_f32 v99, v86, v87
	global_store_dwordx4 v7, v[96:99], s[88:89]
	s_add_u32 s88, s88, s90
	s_addc_u32 s89, s89, 0
	s_waitcnt lgkmcnt(0)
	s_cmp_eq_u32 s91, 0
	s_cbranch_scc1 .Lp0tA_ng3
	v_mul_f32_e32 v88, v88, v10
	v_mul_f32_e32 v89, v89, v11
	v_mul_f32_e32 v90, v90, v12
	v_mul_f32_e32 v91, v91, v13
	v_mul_f32_e32 v92, v92, v14
	v_mul_f32_e32 v93, v93, v15
	v_mul_f32_e32 v94, v94, v16
	v_mul_f32_e32 v95, v95, v17
.Lp0tA_ng3:
	v_cvt_pk_bf16_f32 v100, v88, v89
	v_cvt_pk_bf16_f32 v101, v90, v91
	v_cvt_pk_bf16_f32 v102, v92, v93
	v_cvt_pk_bf16_f32 v103, v94, v95
	global_store_dwordx4 v7, v[100:103], s[88:89]
	s_mov_b32 s100, 1
.Lp0t_loadA:
	s_mov_b32 s85, 0
	s_cmp_lt_u32 s7, 23488
	s_cbranch_scc0 .Lp0t_afterA
	s_cmp_lt_u32 s7, 3904
	s_cbranch_scc1 .Lp0tA_k_in
	s_cmp_lt_u32 s7, 4288
	s_cbranch_scc1 .Lp0tA_k_uq
	s_cmp_lt_u32 s7, 4544
	s_cbranch_scc1 .Lp0tA_k_ukv
	s_cmp_lt_u32 s7, 6592
	s_cbranch_scc1 .Lp0tA_k_out
	s_cmp_lt_u32 s7, 12224
	s_cbranch_scc1 .Lp0tA_k_g
	s_cmp_lt_u32 s7, 17856
	s_cbranch_scc1 .Lp0tA_k_u
	s_sub_u32 s8, s7, 17856
	s_lshr_b32 s9, s8, 6
	s_and_b32 s10, s8, 63
	s_lshl_b32 s10, s10, 5
	s_mov_b64 s[78:79], s[54:55]
	s_add_u32 s80, s28, 0x4c00000
	s_addc_u32 s81, s29, 0
	s_movk_i32 s11, 2048
	s_movk_i32 s60, 5632
	s_mov_b32 s91, 0
	s_mov_b32 s61, s10
	s_mov_b32 s62, 1
	s_branch .Lp0tA_common
.Lp0tA_k_uq:
	s_sub_u32 s8, s7, 3904
	s_mul_hi_u32 s9, s8, 0x5555556
	s_mul_i32 s0, s9, 48
	s_sub_u32 s10, s8, s0
	s_lshl_b32 s10, s10, 5
	s_mov_b64 s[78:79], s[44:45]
	s_mov_b64 s[80:81], s[70:71]
	s_movk_i32 s11, 1536
	s_movk_i32 s60, 512
	s_mov_b32 s91, 1
	s_mov_b64 s[82:83], s[42:43]
	s_mov_b32 s61, s10
	s_mov_b32 s62, 1
	s_mul_i32 s0, s10, 43691
	s_lshr_b32 s0, s0, 23
	s_mul_i32 s0, s0, 192
	s_sub_u32 s3, s10, s0
	s_cmp_lt_u32 s3, 128
	s_cbranch_scc1 .Lp0tA_common
	s_bfe_u32 s3, s3, 0x10005
	s_add_u32 s61, s0, s3
	s_add_u32 s61, s61, 128
	s_mov_b32 s62, 2
	s_branch .Lp0tA_common
.Lp0tA_k_ukv:
	s_sub_u32 s8, s7, 4288
	s_lshr_b32 s9, s8, 6
	s_and_b32 s10, s8, 63
	s_lshl_b32 s10, s10, 5
	s_mov_b64 s[78:79], s[48:49]
	s_mov_b64 s[80:81], s[68:69]
	s_movk_i32 s11, 2048
	s_movk_i32 s60, 256
	s_mov_b32 s91, 1
	s_mov_b64 s[82:83], s[46:47]
	s_mov_b32 s61, s10
	s_mov_b32 s62, 1
	s_branch .Lp0tA_common
.Lp0tA_k_out:
	s_sub_u32 s8, s7, 4544
	s_lshr_b32 s9, s8, 6
	s_and_b32 s10, s8, 63
	s_lshl_b32 s10, s10, 5
	s_mov_b64 s[78:79], s[22:23]
	s_mov_b64 s[80:81], s[66:67]
	s_movk_i32 s11, 2048
	s_movk_i32 s60, 2048
	s_mov_b32 s91, 0
	s_mov_b32 s61, s10
	s_mov_b32 s62, 1
	s_branch .Lp0tA_common
.Lp0tA_k_g:
	s_sub_u32 s8, s7, 6592
	s_mul_hi_u32 s9, s8, 0x1745d18
	s_mul_i32 s0, s9, 176
	s_sub_u32 s10, s8, s0
	s_lshl_b32 s10, s10, 5
	s_mov_b64 s[78:79], s[26:27]
	s_mov_b64 s[80:81], s[64:65]
	s_movk_i32 s11, 5632
	s_movk_i32 s60, 2048
	s_mov_b32 s91, 0
	s_mov_b32 s61, s10
	s_mov_b32 s62, 1
	s_lshr_b32 s0, s10, 7
	s_lshl_b32 s0, s0, 8
	s_and_b32 s3, s10, 127
	s_add_u32 s61, s0, s3
	s_branch .Lp0tA_common
.Lp0tA_k_u:
	s_sub_u32 s8, s7, 12224
	s_mul_hi_u32 s9, s8, 0x1745d18
	s_mul_i32 s0, s9, 176
	s_sub_u32 s10, s8, s0
	s_lshl_b32 s10, s10, 5
	s_mov_b64 s[78:79], s[52:53]
	s_mov_b64 s[80:81], s[64:65]
	s_movk_i32 s11, 5632
	s_movk_i32 s60, 2048
	s_mov_b32 s91, 0
	s_mov_b32 s61, s10
	s_mov_b32 s62, 1
	s_lshr_b32 s0, s10, 7
	s_lshl_b32 s0, s0, 8
	s_and_b32 s3, s10, 127
	s_add_u32 s61, s0, s3
	s_add_u32 s61, s61, 128
	s_branch .Lp0tA_common
.Lp0tA_k_in:
	s_mov_b32 s8, s7
	s_mul_hi_u32 s9, s8, 0x2192e2a
	s_mul_i32 s0, s9, 122
	s_sub_u32 s10, s8, s0
	s_lshl_b32 s10, s10, 5
	s_mov_b64 s[78:79], s[40:41]
	s_mov_b64 s[80:81], s[72:73]
	s_movk_i32 s11, 3904
	s_movk_i32 s60, 2048
	s_mov_b32 s91, 0
	s_mov_b32 s61, s10
	s_mov_b32 s62, 1
	s_cmp_lt_u32 s10, 3840
	s_cbranch_scc1 .Lp0tA_common
	s_bfe_u32 s0, s10, 0x10005
	s_add_u32 s61, s0, 3840
	s_mov_b32 s62, 2
.Lp0tA_common:
	s_lshl_b32 s9, s9, 6
	s_mul_i32 s0, s9, s11
	s_add_u32 s0, s0, s10
	s_lshl_b32 s0, s0, 2
	s_add_u32 s76, s78, s0
	s_addc_u32 s77, s79, 0
	s_lshl_b32 s1, s11, 3
	s_lshl_b32 s3, s11, 2
	v_mul_u32_u24_e32 v6, s3, v1
	v_lshl_add_u32 v6, v0, 2, v6
	s_mul_i32 s0, s61, s60
	s_add_u32 s0, s0, s9
	s_lshl_b32 s0, s0, 1
	s_add_u32 s88, s80, s0
	s_addc_u32 s89, s81, 0
	s_mul_i32 s3, s62, s60
	s_lshl_b32 s90, s3, 4
	s_lshl_b32 s3, s3, 1
	v_mul_u32_u24_e32 v7, s3, v3
	v_lshl_add_u32 v7, v2, 4, v7
	s_cmp_eq_u32 s91, 0
	s_cbranch_scc1 .Lp0tA_nog
	s_lshl_b32 s0, s9, 2
	s_add_u32 s82, s82, s0
	s_addc_u32 s83, s83, 0
	global_load_dwordx4 v[10:13], v9, s[82:83]
	global_load_dwordx4 v[14:17], v9, s[82:83] offset:16
.Lp0tA_nog:
	global_load_dword v32, v6, s[76:77]
	s_add_u32 s76, s76, s1
	s_addc_u32 s77, s77, 0
	global_load_dword v33, v6, s[76:77]
	s_add_u32 s76, s76, s1
	s_addc_u32 s77, s77, 0
	global_load_dword v34, v6, s[76:77]
	s_add_u32 s76, s76, s1
	s_addc_u32 s77, s77, 0
	global_load_dword v35, v6, s[76:77]
	s_add_u32 s76, s76, s1
	s_addc_u32 s77, s77, 0
	global_load_dword v36, v6, s[76:77]
	s_add_u32 s76, s76, s1
	s_addc_u32 s77, s77, 0
	global_load_dword v37, v6, s[76:77]
	s_add_u32 s76, s76, s1
	s_addc_u32 s77, s77, 0
	global_load_dword v38, v6, s[76:77]
	s_add_u32 s76, s76, s1
	s_addc_u32 s77, s77, 0
	global_load_dword v39, v6, s[76:77]
	s_add_u32 s76, s76, s1
	s_addc_u32 s77, s77, 0
	global_load_dword v40, v6, s[76:77]
	s_add_u32 s76, s76, s1
	s_addc_u32 s77, s77, 0
	global_load_dword v41, v6, s[76:77]
	s_add_u32 s76, s76, s1
	s_addc_u32 s77, s77, 0
	global_load_dword v42, v6, s[76:77]
	s_add_u32 s76, s76, s1
	s_addc_u32 s77, s77, 0
	global_load_dword v43, v6, s[76:77]
	s_add_u32 s76, s76, s1
	s_addc_u32 s77, s77, 0
	global_load_dword v44, v6, s[76:77]
	s_add_u32 s76, s76, s1
	s_addc_u32 s77, s77, 0
	global_load_dword v45, v6, s[76:77]
	s_add_u32 s76, s76, s1
	s_addc_u32 s77, s77, 0
	global_load_dword v46, v6, s[76:77]
	s_add_u32 s76, s76, s1
	s_addc_u32 s77, s77, 0
	global_load_dword v47, v6, s[76:77]
	s_add_u32 s76, s76, s1
	s_addc_u32 s77, s77, 0
	global_load_dword v48, v6, s[76:77]
	s_add_u32 s76, s76, s1
	s_addc_u32 s77, s77, 0
	global_load_dword v49, v6, s[76:77]
	s_add_u32 s76, s76, s1
	s_addc_u32 s77, s77, 0
	global_load_dword v50, v6, s[76:77]
	s_add_u32 s76, s76, s1
	s_addc_u32 s77, s77, 0
	global_load_dword v51, v6, s[76:77]
	s_add_u32 s76, s76, s1
	s_addc_u32 s77, s77, 0
	global_load_dword v52, v6, s[76:77]
	s_add_u32 s76, s76, s1
	s_addc_u32 s77, s77, 0
	global_load_dword v53, v6, s[76:77]
	s_add_u32 s76, s76, s1
	s_addc_u32 s77, s77, 0
	global_load_dword v54, v6, s[76:77]
	s_add_u32 s76, s76, s1
	s_addc_u32 s77, s77, 0
	global_load_dword v55, v6, s[76:77]
	s_add_u32 s76, s76, s1
	s_addc_u32 s77, s77, 0
	global_load_dword v56, v6, s[76:77]
	s_add_u32 s76, s76, s1
	s_addc_u32 s77, s77, 0
	global_load_dword v57, v6, s[76:77]
	s_add_u32 s76, s76, s1
	s_addc_u32 s77, s77, 0
	global_load_dword v58, v6, s[76:77]
	s_add_u32 s76, s76, s1
	s_addc_u32 s77, s77, 0
	global_load_dword v59, v6, s[76:77]
	s_add_u32 s76, s76, s1
	s_addc_u32 s77, s77, 0
	global_load_dword v60, v6, s[76:77]
	s_add_u32 s76, s76, s1
	s_addc_u32 s77, s77, 0
	global_load_dword v61, v6, s[76:77]
	s_add_u32 s76, s76, s1
	s_addc_u32 s77, s77, 0
	global_load_dword v62, v6, s[76:77]
	s_add_u32 s76, s76, s1
	s_addc_u32 s77, s77, 0
	global_load_dword v63, v6, s[76:77]
	s_mov_b32 s85, 1
	s_add_u32 s7, s7, s6
.Lp0t_afterA:
	s_cmp_eq_u32 s101, 0
	s_cbranch_scc1 .Lp0t_loadB
	s_cmp_eq_u32 s84, 0
	s_cbranch_scc1 .Lp0t_done
.Lp0t_stageB:
	s_lshl_b32 s1, s85, 1
	s_add_u32 s1, s1, s100
	s_cmp_eq_u32 s1, 3
	s_cbranch_scc1 .Lp0tB_w36
	s_cmp_eq_u32 s1, 2
	s_cbranch_scc1 .Lp0tB_w32
	s_cmp_eq_u32 s1, 1
	s_cbranch_scc1 .Lp0tB_w4
	s_waitcnt vmcnt(0)
	s_branch .Lp0tB_go

.Lp0tB_go:
	ds_write_b32 v4, v128
	ds_write_b32 v4, v129 offset:264
	ds_write_b32 v4, v130 offset:528
	ds_write_b32 v4, v131 offset:792
	ds_write_b32 v4, v132 offset:1056
	ds_write_b32 v4, v133 offset:1320
	ds_write_b32 v4, v134 offset:1584
	ds_write_b32 v4, v135 offset:1848
	ds_write_b32 v4, v136 offset:2112
	ds_write_b32 v4, v137 offset:2376
	ds_write_b32 v4, v138 offset:2640
	ds_write_b32 v4, v139 offset:2904
	ds_write_b32 v4, v140 offset:3168
	ds_write_b32 v4, v141 offset:3432
	ds_write_b32 v4, v142 offset:3696
	ds_write_b32 v4, v143 offset:3960
	ds_write_b32 v4, v144 offset:4224
	ds_write_b32 v4, v145 offset:4488
	ds_write_b32 v4, v146 offset:4752
	ds_write_b32 v4, v147 offset:5016
	ds_write_b32 v4, v148 offset:5280
	ds_write_b32 v4, v149 offset:5544
	ds_write_b32 v4, v150 offset:5808
	ds_write_b32 v4, v151 offset:6072
	ds_write_b32 v4, v152 offset:6336
	ds_write_b32 v4, v153 offset:6600
	ds_write_b32 v4, v154 offset:6864
	ds_write_b32 v4, v155 offset:7128
	ds_write_b32 v4, v156 offset:7392
	ds_write_b32 v4, v157 offset:7656
	ds_write_b32 v4, v158 offset:7920
	ds_write_b32 v4, v159 offset:8184
	s_waitcnt lgkmcnt(0)
	ds_read2_b32 v[64:65], v5 offset0:0 offset1:33
	ds_read2_b32 v[66:67], v5 offset0:66 offset1:99
	ds_read2_b32 v[68:69], v5 offset0:132 offset1:165
	ds_read2_b32 v[70:71], v5 offset0:198 offset1:231
	ds_read2_b32 v[72:73], v5 offset0:8 offset1:41
	ds_read2_b32 v[74:75], v5 offset0:74 offset1:107
	ds_read2_b32 v[76:77], v5 offset0:140 offset1:173
	ds_read2_b32 v[78:79], v5 offset0:206 offset1:239
	ds_read2_b32 v[80:81], v5 offset0:16 offset1:49
	ds_read2_b32 v[82:83], v5 offset0:82 offset1:115
	ds_read2_b32 v[84:85], v5 offset0:148 offset1:181
	ds_read2_b32 v[86:87], v5 offset0:214 offset1:247
	ds_read2_b32 v[88:89], v5 offset0:24 offset1:57
	ds_read2_b32 v[90:91], v5 offset0:90 offset1:123
	ds_read2_b32 v[92:93], v5 offset0:156 offset1:189
	ds_read2_b32 v[94:95], v5 offset0:222 offset1:255
	s_waitcnt lgkmcnt(12)
	s_cmp_eq_u32 s87, 0
	s_cbranch_scc1 .Lp0tB_ng0
	v_mul_f32_e32 v64, v64, v104
	v_mul_f32_e32 v65, v65, v105
	v_mul_f32_e32 v66, v66, v106
	v_mul_f32_e32 v67, v67, v107
	v_mul_f32_e32 v68, v68, v108
	v_mul_f32_e32 v69, v69, v109
	v_mul_f32_e32 v70, v70, v110
	v_mul_f32_e32 v71, v71, v111
.Lp0tB_ng0:
	v_cvt_pk_bf16_f32 v96, v64, v65
	v_cvt_pk_bf16_f32 v97, v66, v67
	v_cvt_pk_bf16_f32 v98, v68, v69
	v_cvt_pk_bf16_f32 v99, v70, v71
	global_store_dwordx4 v26, v[96:99], s[92:93]
	s_add_u32 s92, s92, s5
	s_addc_u32 s93, s93, 0
	s_waitcnt lgkmcnt(8)
	s_cmp_eq_u32 s87, 0
	s_cbranch_scc1 .Lp0tB_ng1
	v_mul_f32_e32 v72, v72, v104
	v_mul_f32_e32 v73, v73, v105
	v_mul_f32_e32 v74, v74, v106
	v_mul_f32_e32 v75, v75, v107
	v_mul_f32_e32 v76, v76, v108
	v_mul_f32_e32 v77, v77, v109
	v_mul_f32_e32 v78, v78, v110
	v_mul_f32_e32 v79, v79, v111
.Lp0tB_ng1:
	v_cvt_pk_bf16_f32 v100, v72, v73
	v_cvt_pk_bf16_f32 v101, v74, v75
	v_cvt_pk_bf16_f32 v102, v76, v77
	v_cvt_pk_bf16_f32 v103, v78, v79
	global_store_dwordx4 v26, v[100:103], s[92:93]
	s_add_u32 s92, s92, s5
	s_addc_u32 s93, s93, 0
	s_waitcnt lgkmcnt(4)
	s_cmp_eq_u32 s87, 0
	s_cbranch_scc1 .Lp0tB_ng2
	v_mul_f32_e32 v80, v80, v104
	v_mul_f32_e32 v81, v81, v105
	v_mul_f32_e32 v82, v82, v106
	v_mul_f32_e32 v83, v83, v107
	v_mul_f32_e32 v84, v84, v108
	v_mul_f32_e32 v85, v85, v109
	v_mul_f32_e32 v86, v86, v110
	v_mul_f32_e32 v87, v87, v111
.Lp0tB_ng2:
	v_cvt_pk_bf16_f32 v96, v80, v81
	v_cvt_pk_bf16_f32 v97, v82, v83
	v_cvt_pk_bf16_f32 v98, v84, v85
	v_cvt_pk_bf16_f32 v99, v86, v87
	global_store_dwordx4 v26, v[96:99], s[92:93]
	s_add_u32 s92, s92, s5
	s_addc_u32 s93, s93, 0
	s_waitcnt lgkmcnt(0)
	s_cmp_eq_u32 s87, 0
	s_cbranch_scc1 .Lp0tB_ng3
	v_mul_f32_e32 v88, v88, v104
	v_mul_f32_e32 v89, v89, v105
	v_mul_f32_e32 v90, v90, v106
	v_mul_f32_e32 v91, v91, v107
	v_mul_f32_e32 v92, v92, v108
	v_mul_f32_e32 v93, v93, v109
	v_mul_f32_e32 v94, v94, v110
	v_mul_f32_e32 v95, v95, v111
.Lp0tB_ng3:
	v_cvt_pk_bf16_f32 v100, v88, v89
	v_cvt_pk_bf16_f32 v101, v90, v91
	v_cvt_pk_bf16_f32 v102, v92, v93
	v_cvt_pk_bf16_f32 v103, v94, v95
	global_store_dwordx4 v26, v[100:103], s[92:93]
	s_mov_b32 s100, 1
.Lp0t_loadB:
	s_mov_b32 s84, 0
	s_cmp_lt_u32 s7, 23488
	s_cbranch_scc0 .Lp0t_afterB
	s_cmp_lt_u32 s7, 3904
	s_cbranch_scc1 .Lp0tB_k_in
	s_cmp_lt_u32 s7, 4288
	s_cbranch_scc1 .Lp0tB_k_uq
	s_cmp_lt_u32 s7, 4544
	s_cbranch_scc1 .Lp0tB_k_ukv
	s_cmp_lt_u32 s7, 6592
	s_cbranch_scc1 .Lp0tB_k_out
	s_cmp_lt_u32 s7, 12224
	s_cbranch_scc1 .Lp0tB_k_g
	s_cmp_lt_u32 s7, 17856
	s_cbranch_scc1 .Lp0tB_k_u
	s_sub_u32 s8, s7, 17856
	s_lshr_b32 s9, s8, 6
	s_and_b32 s10, s8, 63
	s_lshl_b32 s10, s10, 5
	s_mov_b64 s[78:79], s[54:55]
	s_add_u32 s80, s28, 0x4c00000
	s_addc_u32 s81, s29, 0
	s_movk_i32 s11, 2048
	s_movk_i32 s60, 5632
	s_mov_b32 s87, 0
	s_mov_b32 s61, s10
	s_mov_b32 s62, 1
	s_branch .Lp0tB_common
.Lp0tB_k_uq:
	s_sub_u32 s8, s7, 3904
	s_mul_hi_u32 s9, s8, 0x5555556
	s_mul_i32 s0, s9, 48
	s_sub_u32 s10, s8, s0
	s_lshl_b32 s10, s10, 5
	s_mov_b64 s[78:79], s[44:45]
	s_mov_b64 s[80:81], s[70:71]
	s_movk_i32 s11, 1536
	s_movk_i32 s60, 512
	s_mov_b32 s87, 1
	s_mov_b64 s[82:83], s[42:43]
	s_mov_b32 s61, s10
	s_mov_b32 s62, 1
	s_mul_i32 s0, s10, 43691
	s_lshr_b32 s0, s0, 23
	s_mul_i32 s0, s0, 192
	s_sub_u32 s3, s10, s0
	s_cmp_lt_u32 s3, 128
	s_cbranch_scc1 .Lp0tB_common
	s_bfe_u32 s3, s3, 0x10005
	s_add_u32 s61, s0, s3
	s_add_u32 s61, s61, 128
	s_mov_b32 s62, 2
	s_branch .Lp0tB_common
.Lp0tB_k_ukv:
	s_sub_u32 s8, s7, 4288
	s_lshr_b32 s9, s8, 6
	s_and_b32 s10, s8, 63
	s_lshl_b32 s10, s10, 5
	s_mov_b64 s[78:79], s[48:49]
	s_mov_b64 s[80:81], s[68:69]
	s_movk_i32 s11, 2048
	s_movk_i32 s60, 256
	s_mov_b32 s87, 1
	s_mov_b64 s[82:83], s[46:47]
	s_mov_b32 s61, s10
	s_mov_b32 s62, 1
	s_branch .Lp0tB_common
.Lp0tB_k_out:
	s_sub_u32 s8, s7, 4544
	s_lshr_b32 s9, s8, 6
	s_and_b32 s10, s8, 63
	s_lshl_b32 s10, s10, 5
	s_mov_b64 s[78:79], s[22:23]
	s_mov_b64 s[80:81], s[66:67]
	s_movk_i32 s11, 2048
	s_movk_i32 s60, 2048
	s_mov_b32 s87, 0
	s_mov_b32 s61, s10
	s_mov_b32 s62, 1
	s_branch .Lp0tB_common
.Lp0tB_k_g:
	s_sub_u32 s8, s7, 6592
	s_mul_hi_u32 s9, s8, 0x1745d18
	s_mul_i32 s0, s9, 176
	s_sub_u32 s10, s8, s0
	s_lshl_b32 s10, s10, 5
	s_mov_b64 s[78:79], s[26:27]
	s_mov_b64 s[80:81], s[64:65]
	s_movk_i32 s11, 5632
	s_movk_i32 s60, 2048
	s_mov_b32 s87, 0
	s_mov_b32 s61, s10
	s_mov_b32 s62, 1
	s_lshr_b32 s0, s10, 7
	s_lshl_b32 s0, s0, 8
	s_and_b32 s3, s10, 127
	s_add_u32 s61, s0, s3
	s_branch .Lp0tB_common
.Lp0tB_k_u:
	s_sub_u32 s8, s7, 12224
	s_mul_hi_u32 s9, s8, 0x1745d18
	s_mul_i32 s0, s9, 176
	s_sub_u32 s10, s8, s0
	s_lshl_b32 s10, s10, 5
	s_mov_b64 s[78:79], s[52:53]
	s_mov_b64 s[80:81], s[64:65]
	s_movk_i32 s11, 5632
	s_movk_i32 s60, 2048
	s_mov_b32 s87, 0
	s_mov_b32 s61, s10
	s_mov_b32 s62, 1
	s_lshr_b32 s0, s10, 7
	s_lshl_b32 s0, s0, 8
	s_and_b32 s3, s10, 127
	s_add_u32 s61, s0, s3
	s_add_u32 s61, s61, 128
	s_branch .Lp0tB_common
.Lp0tB_k_in:
	s_mov_b32 s8, s7
	s_mul_hi_u32 s9, s8, 0x2192e2a
	s_mul_i32 s0, s9, 122
	s_sub_u32 s10, s8, s0
	s_lshl_b32 s10, s10, 5
	s_mov_b64 s[78:79], s[40:41]
	s_mov_b64 s[80:81], s[72:73]
	s_movk_i32 s11, 3904
	s_movk_i32 s60, 2048
	s_mov_b32 s87, 0
	s_mov_b32 s61, s10
	s_mov_b32 s62, 1
	s_cmp_lt_u32 s10, 3840
	s_cbranch_scc1 .Lp0tB_common
	s_bfe_u32 s0, s10, 0x10005
	s_add_u32 s61, s0, 3840
	s_mov_b32 s62, 2
.Lp0tB_common:
	s_lshl_b32 s9, s9, 6
	s_mul_i32 s0, s9, s11
	s_add_u32 s0, s0, s10
	s_lshl_b32 s0, s0, 2
	s_add_u32 s76, s78, s0
	s_addc_u32 s77, s79, 0
	s_lshl_b32 s1, s11, 3
	s_lshl_b32 s3, s11, 2
	v_mul_u32_u24_e32 v6, s3, v1
	v_lshl_add_u32 v6, v0, 2, v6
	s_mul_i32 s0, s61, s60
	s_add_u32 s0, s0, s9
	s_lshl_b32 s0, s0, 1
	s_add_u32 s92, s80, s0
	s_addc_u32 s93, s81, 0
	s_mul_i32 s3, s62, s60
	s_lshl_b32 s5, s3, 4
	s_lshl_b32 s3, s3, 1
	v_mul_u32_u24_e32 v26, s3, v3
	v_lshl_add_u32 v26, v2, 4, v26
	s_cmp_eq_u32 s87, 0
	s_cbranch_scc1 .Lp0tB_nog
	s_lshl_b32 s0, s9, 2
	s_add_u32 s82, s82, s0
	s_addc_u32 s83, s83, 0
	global_load_dwordx4 v[104:107], v9, s[82:83]
	global_load_dwordx4 v[108:111], v9, s[82:83] offset:16
.Lp0tB_nog:
	global_load_dword v128, v6, s[76:77]
	s_add_u32 s76, s76, s1
	s_addc_u32 s77, s77, 0
	global_load_dword v129, v6, s[76:77]
	s_add_u32 s76, s76, s1
	s_addc_u32 s77, s77, 0
	global_load_dword v130, v6, s[76:77]
	s_add_u32 s76, s76, s1
	s_addc_u32 s77, s77, 0
	global_load_dword v131, v6, s[76:77]
	s_add_u32 s76, s76, s1
	s_addc_u32 s77, s77, 0
	global_load_dword v132, v6, s[76:77]
	s_add_u32 s76, s76, s1
	s_addc_u32 s77, s77, 0
	global_load_dword v133, v6, s[76:77]
	s_add_u32 s76, s76, s1
	s_addc_u32 s77, s77, 0
	global_load_dword v134, v6, s[76:77]
	s_add_u32 s76, s76, s1
	s_addc_u32 s77, s77, 0
	global_load_dword v135, v6, s[76:77]
	s_add_u32 s76, s76, s1
	s_addc_u32 s77, s77, 0
	global_load_dword v136, v6, s[76:77]
	s_add_u32 s76, s76, s1
	s_addc_u32 s77, s77, 0
	global_load_dword v137, v6, s[76:77]
	s_add_u32 s76, s76, s1
	s_addc_u32 s77, s77, 0
	global_load_dword v138, v6, s[76:77]
	s_add_u32 s76, s76, s1
	s_addc_u32 s77, s77, 0
	global_load_dword v139, v6, s[76:77]
	s_add_u32 s76, s76, s1
	s_addc_u32 s77, s77, 0
	global_load_dword v140, v6, s[76:77]
	s_add_u32 s76, s76, s1
	s_addc_u32 s77, s77, 0
	global_load_dword v141, v6, s[76:77]
	s_add_u32 s76, s76, s1
	s_addc_u32 s77, s77, 0
	global_load_dword v142, v6, s[76:77]
	s_add_u32 s76, s76, s1
	s_addc_u32 s77, s77, 0
	global_load_dword v143, v6, s[76:77]
	s_add_u32 s76, s76, s1
	s_addc_u32 s77, s77, 0
	global_load_dword v144, v6, s[76:77]
	s_add_u32 s76, s76, s1
	s_addc_u32 s77, s77, 0
	global_load_dword v145, v6, s[76:77]
	s_add_u32 s76, s76, s1
	s_addc_u32 s77, s77, 0
	global_load_dword v146, v6, s[76:77]
	s_add_u32 s76, s76, s1
	s_addc_u32 s77, s77, 0
	global_load_dword v147, v6, s[76:77]
	s_add_u32 s76, s76, s1
	s_addc_u32 s77, s77, 0
	global_load_dword v148, v6, s[76:77]
	s_add_u32 s76, s76, s1
	s_addc_u32 s77, s77, 0
	global_load_dword v149, v6, s[76:77]
	s_add_u32 s76, s76, s1
	s_addc_u32 s77, s77, 0
	global_load_dword v150, v6, s[76:77]
	s_add_u32 s76, s76, s1
	s_addc_u32 s77, s77, 0
	global_load_dword v151, v6, s[76:77]
	s_add_u32 s76, s76, s1
	s_addc_u32 s77, s77, 0
	global_load_dword v152, v6, s[76:77]
	s_add_u32 s76, s76, s1
	s_addc_u32 s77, s77, 0
	global_load_dword v153, v6, s[76:77]
	s_add_u32 s76, s76, s1
	s_addc_u32 s77, s77, 0
	global_load_dword v154, v6, s[76:77]
	s_add_u32 s76, s76, s1
	s_addc_u32 s77, s77, 0
	global_load_dword v155, v6, s[76:77]
	s_add_u32 s76, s76, s1
	s_addc_u32 s77, s77, 0
	global_load_dword v156, v6, s[76:77]
	s_add_u32 s76, s76, s1
	s_addc_u32 s77, s77, 0
	global_load_dword v157, v6, s[76:77]
	s_add_u32 s76, s76, s1
	s_addc_u32 s77, s77, 0
	global_load_dword v158, v6, s[76:77]
	s_add_u32 s76, s76, s1
	s_addc_u32 s77, s77, 0
	global_load_dword v159, v6, s[76:77]
	s_mov_b32 s84, 1
	s_add_u32 s7, s7, s6
.Lp0t_afterB:
	s_cmp_eq_u32 s101, 0
	s_cbranch_scc0 .Lp0t_cont
	s_mov_b32 s101, 1
	s_cmp_eq_u32 s85, 0
	s_cbranch_scc1 .Lp0t_done
	s_branch .Lp0t_stageA
.Lp0t_cont:
	s_cmp_eq_u32 s85, 0
	s_cbranch_scc0 .Lp0t_stageA
.Lp0t_done:
.LBB0_91:
	s_cmpk_gt_i32 s4, 0x3fff
	s_cbranch_scc1 .LBB0_94
	s_waitcnt lgkmcnt(0)
	v_lshlrev_b32_e32 v0, 4, v204
	v_lshlrev_b32_e32 v1, 3, v204
	v_mov_b32_e32 v28, 0x358637bd
	s_add_u32 s0, s38, 0x1000
	s_addc_u32 s1, s39, 0
	global_load_dwordx4 v[96:99], v0, s[0:1] offset:-4096
	global_load_dwordx4 v[100:103], v0, s[0:1] offset:-3072
	global_load_dwordx4 v[104:107], v0, s[0:1] offset:-2048
	global_load_dwordx4 v[108:111], v0, s[0:1] offset:-1024
	global_load_dwordx4 v[112:115], v0, s[0:1] offset:0
	global_load_dwordx4 v[116:119], v0, s[0:1] offset:1024
	global_load_dwordx4 v[120:123], v0, s[0:1] offset:2048
	global_load_dwordx4 v[124:127], v0, s[0:1] offset:3072
	s_lshl_b32 s3, s4, 13
	s_add_u32 s8, s36, s3
	s_addc_u32 s9, s37, 0
	s_add_u32 s8, s8, 0x1000
	s_addc_u32 s9, s9, 0
	s_lshl_b32 s3, s4, 12
	s_add_u32 s10, s28, s3
	s_addc_u32 s11, s29, 0
	s_add_u32 s10, s10, 0x6200000
	s_addc_u32 s11, s11, 0
	s_lshl_b32 s7, s6, 13
	s_lshl_b32 s5, s6, 12
	global_load_dwordx4 v[32:35], v0, s[8:9] offset:-4096
	global_load_dwordx4 v[36:39], v0, s[8:9] offset:-3072
	global_load_dwordx4 v[40:43], v0, s[8:9] offset:-2048
	global_load_dwordx4 v[44:47], v0, s[8:9] offset:-1024
	global_load_dwordx4 v[48:51], v0, s[8:9] offset:0
	global_load_dwordx4 v[52:55], v0, s[8:9] offset:1024
	global_load_dwordx4 v[56:59], v0, s[8:9] offset:2048
	global_load_dwordx4 v[60:63], v0, s[8:9] offset:3072
	s_mov_b32 s3, 0
.Lp0r_loop:
	s_add_i32 s4, s4, s6
	s_cmp_lt_i32 s4, 0x4000
	s_cselect_b32 s0, 1, 0
	s_cbranch_scc0 .Lp0r_a_nonext
	s_add_u32 s8, s8, s7
	s_addc_u32 s9, s9, 0
	global_load_dwordx4 v[64:67], v0, s[8:9] offset:-4096
	global_load_dwordx4 v[68:71], v0, s[8:9] offset:-3072
	global_load_dwordx4 v[72:75], v0, s[8:9] offset:-2048
	global_load_dwordx4 v[76:79], v0, s[8:9] offset:-1024
	global_load_dwordx4 v[80:83], v0, s[8:9] offset:0
	global_load_dwordx4 v[84:87], v0, s[8:9] offset:1024
	global_load_dwordx4 v[88:91], v0, s[8:9] offset:2048
	global_load_dwordx4 v[92:95], v0, s[8:9] offset:3072
.Lp0r_a_nonext:
	s_add_u32 s1, s0, s3
	s_cmp_eq_u32 s1, 2
	s_cbranch_scc1 .Lp0r_a_w16
	s_cmp_eq_u32 s1, 1
	s_cbranch_scc1 .Lp0r_a_w8
	s_waitcnt vmcnt(0)
	s_branch .Lp0r_a_go
.Lp0r_a_w16:
	s_waitcnt vmcnt(16)
	s_branch .Lp0r_a_go
.Lp0r_a_w8:
	s_waitcnt vmcnt(8)
.Lp0r_a_go:
	v_pk_mul_f32 v[2:3], v[32:33], v[32:33]
	v_pk_mul_f32 v[4:5], v[34:35], v[34:35]
	v_pk_fma_f32 v[2:3], v[36:37], v[36:37], v[2:3]
	v_pk_fma_f32 v[4:5], v[38:39], v[38:39], v[4:5]
	v_pk_fma_f32 v[2:3], v[40:41], v[40:41], v[2:3]
	v_pk_fma_f32 v[4:5], v[42:43], v[42:43], v[4:5]
	v_pk_fma_f32 v[2:3], v[44:45], v[44:45], v[2:3]
	v_pk_fma_f32 v[4:5], v[46:47], v[46:47], v[4:5]
	v_pk_fma_f32 v[2:3], v[48:49], v[48:49], v[2:3]
	v_pk_fma_f32 v[4:5], v[50:51], v[50:51], v[4:5]
	v_pk_fma_f32 v[2:3], v[52:53], v[52:53], v[2:3]
	v_pk_fma_f32 v[4:5], v[54:55], v[54:55], v[4:5]
	v_pk_fma_f32 v[2:3], v[56:57], v[56:57], v[2:3]
	v_pk_fma_f32 v[4:5], v[58:59], v[58:59], v[4:5]
	v_pk_fma_f32 v[2:3], v[60:61], v[60:61], v[2:3]
	v_pk_fma_f32 v[4:5], v[62:63], v[62:63], v[4:5]
	v_pk_add_f32 v[2:3], v[2:3], v[4:5]
	s_nop 0
	v_add_f32_e32 v2, v2, v3
	s_nop 1
	v_add_f32_dpp v3, v2, v2 quad_perm:[1,0,3,2] row_mask:0xf bank_mask:0xf
	s_nop 1
	v_add_f32_dpp v2, v3, v3 quad_perm:[2,3,0,1] row_mask:0xf bank_mask:0xf
	s_nop 1
	v_add_f32_dpp v3, v2, v2 row_ror:4 row_mask:0xf bank_mask:0xf
	s_nop 1
	v_add_f32_dpp v2, v3, v3 row_ror:8 row_mask:0xf bank_mask:0xf
	s_nop 1
	v_readlane_b32 s100, v2, 0
	v_readlane_b32 s101, v2, 16
	v_readlane_b32 vcc_lo, v2, 32
	v_readlane_b32 vcc_hi, v2, 48
	v_mov_b32_e32 v3, s100
	v_add_f32_e32 v3, s101, v3
	v_add_f32_e32 v3, vcc_lo, v3
	v_add_f32_e32 v3, vcc_hi, v3
	v_fmamk_f32 v2, v3, 0x3a000000, v28
	v_mul_f32_e32 v3, 0x4b800000, v2
	v_cmp_gt_f32_e32 vcc, 0x800000, v2
	s_nop 1
	v_cndmask_b32_e32 v2, v2, v3, vcc
	v_rsq_f32_e32 v2, v2
	s_nop 0
	v_mul_f32_e32 v3, 0x45800000, v2
	v_cndmask_b32_e32 v2, v2, v3, vcc
	v_pk_mul_f32 v[32:33], v[32:33], v[2:3] op_sel_hi:[1,0]
	v_pk_mul_f32 v[34:35], v[34:35], v[2:3] op_sel_hi:[1,0]
	v_pk_mul_f32 v[32:33], v[32:33], v[96:97]
	v_pk_mul_f32 v[34:35], v[34:35], v[98:99]
	v_cvt_pk_bf16_f32 v6, v32, v33
	v_cvt_pk_bf16_f32 v7, v34, v35
	global_store_dwordx2 v1, v[6:7], s[10:11]
	v_pk_mul_f32 v[36:37], v[36:37], v[2:3] op_sel_hi:[1,0]
	v_pk_mul_f32 v[38:39], v[38:39], v[2:3] op_sel_hi:[1,0]
	v_pk_mul_f32 v[36:37], v[36:37], v[100:101]
	v_pk_mul_f32 v[38:39], v[38:39], v[102:103]
	v_cvt_pk_bf16_f32 v8, v36, v37
	v_cvt_pk_bf16_f32 v9, v38, v39
	global_store_dwordx2 v1, v[8:9], s[10:11] offset:512
	v_pk_mul_f32 v[40:41], v[40:41], v[2:3] op_sel_hi:[1,0]
	v_pk_mul_f32 v[42:43], v[42:43], v[2:3] op_sel_hi:[1,0]
	v_pk_mul_f32 v[40:41], v[40:41], v[104:105]
	v_pk_mul_f32 v[42:43], v[42:43], v[106:107]
	v_cvt_pk_bf16_f32 v6, v40, v41
	v_cvt_pk_bf16_f32 v7, v42, v43
	global_store_dwordx2 v1, v[6:7], s[10:11] offset:1024
	v_pk_mul_f32 v[44:45], v[44:45], v[2:3] op_sel_hi:[1,0]
	v_pk_mul_f32 v[46:47], v[46:47], v[2:3] op_sel_hi:[1,0]
	v_pk_mul_f32 v[44:45], v[44:45], v[108:109]
	v_pk_mul_f32 v[46:47], v[46:47], v[110:111]
	v_cvt_pk_bf16_f32 v8, v44, v45
	v_cvt_pk_bf16_f32 v9, v46, v47
	global_store_dwordx2 v1, v[8:9], s[10:11] offset:1536
	v_pk_mul_f32 v[48:49], v[48:49], v[2:3] op_sel_hi:[1,0]
	v_pk_mul_f32 v[50:51], v[50:51], v[2:3] op_sel_hi:[1,0]
	v_pk_mul_f32 v[48:49], v[48:49], v[112:113]
	v_pk_mul_f32 v[50:51], v[50:51], v[114:115]
	v_cvt_pk_bf16_f32 v6, v48, v49
	v_cvt_pk_bf16_f32 v7, v50, v51
	global_store_dwordx2 v1, v[6:7], s[10:11] offset:2048
	v_pk_mul_f32 v[52:53], v[52:53], v[2:3] op_sel_hi:[1,0]
	v_pk_mul_f32 v[54:55], v[54:55], v[2:3] op_sel_hi:[1,0]
	v_pk_mul_f32 v[52:53], v[52:53], v[116:117]
	v_pk_mul_f32 v[54:55], v[54:55], v[118:119]
	v_cvt_pk_bf16_f32 v8, v52, v53
	v_cvt_pk_bf16_f32 v9, v54, v55
	global_store_dwordx2 v1, v[8:9], s[10:11] offset:2560
	v_pk_mul_f32 v[56:57], v[56:57], v[2:3] op_sel_hi:[1,0]
	v_pk_mul_f32 v[58:59], v[58:59], v[2:3] op_sel_hi:[1,0]
	v_pk_mul_f32 v[56:57], v[56:57], v[120:121]
	v_pk_mul_f32 v[58:59], v[58:59], v[122:123]
	v_cvt_pk_bf16_f32 v6, v56, v57
	v_cvt_pk_bf16_f32 v7, v58, v59
	global_store_dwordx2 v1, v[6:7], s[10:11] offset:3072
	v_pk_mul_f32 v[60:61], v[60:61], v[2:3] op_sel_hi:[1,0]
	v_pk_mul_f32 v[62:63], v[62:63], v[2:3] op_sel_hi:[1,0]
	v_pk_mul_f32 v[60:61], v[60:61], v[124:125]
	v_pk_mul_f32 v[62:63], v[62:63], v[126:127]
	v_cvt_pk_bf16_f32 v8, v60, v61
	v_cvt_pk_bf16_f32 v9, v62, v63
	global_store_dwordx2 v1, v[8:9], s[10:11] offset:3584
	s_add_u32 s10, s10, s5
	s_addc_u32 s11, s11, 0
	s_mov_b32 s3, 1
	s_cmp_eq_u32 s0, 0
	s_cbranch_scc1 .LBB0_94
	s_add_i32 s4, s4, s6
	s_cmp_lt_i32 s4, 0x4000
	s_cselect_b32 s0, 1, 0
	s_cbranch_scc0 .Lp0r_b_nonext
	s_add_u32 s8, s8, s7
	s_addc_u32 s9, s9, 0
	global_load_dwordx4 v[32:35], v0, s[8:9] offset:-4096
	global_load_dwordx4 v[36:39], v0, s[8:9] offset:-3072
	global_load_dwordx4 v[40:43], v0, s[8:9] offset:-2048
	global_load_dwordx4 v[44:47], v0, s[8:9] offset:-1024
	global_load_dwordx4 v[48:51], v0, s[8:9] offset:0
	global_load_dwordx4 v[52:55], v0, s[8:9] offset:1024
	global_load_dwordx4 v[56:59], v0, s[8:9] offset:2048
	global_load_dwordx4 v[60:63], v0, s[8:9] offset:3072

.Lp0r_b_go:
	v_pk_mul_f32 v[2:3], v[64:65], v[64:65]
	v_pk_mul_f32 v[4:5], v[66:67], v[66:67]
	v_pk_fma_f32 v[2:3], v[68:69], v[68:69], v[2:3]
	v_pk_fma_f32 v[4:5], v[70:71], v[70:71], v[4:5]
	v_pk_fma_f32 v[2:3], v[72:73], v[72:73], v[2:3]
	v_pk_fma_f32 v[4:5], v[74:75], v[74:75], v[4:5]
	v_pk_fma_f32 v[2:3], v[76:77], v[76:77], v[2:3]
	v_pk_fma_f32 v[4:5], v[78:79], v[78:79], v[4:5]
	v_pk_fma_f32 v[2:3], v[80:81], v[80:81], v[2:3]
	v_pk_fma_f32 v[4:5], v[82:83], v[82:83], v[4:5]
	v_pk_fma_f32 v[2:3], v[84:85], v[84:85], v[2:3]
	v_pk_fma_f32 v[4:5], v[86:87], v[86:87], v[4:5]
	v_pk_fma_f32 v[2:3], v[88:89], v[88:89], v[2:3]
	v_pk_fma_f32 v[4:5], v[90:91], v[90:91], v[4:5]
	v_pk_fma_f32 v[2:3], v[92:93], v[92:93], v[2:3]
	v_pk_fma_f32 v[4:5], v[94:95], v[94:95], v[4:5]
	v_pk_add_f32 v[2:3], v[2:3], v[4:5]
	s_nop 0
	v_add_f32_e32 v2, v2, v3
	s_nop 1
	v_add_f32_dpp v3, v2, v2 quad_perm:[1,0,3,2] row_mask:0xf bank_mask:0xf
	s_nop 1
	v_add_f32_dpp v2, v3, v3 quad_perm:[2,3,0,1] row_mask:0xf bank_mask:0xf
	s_nop 1
	v_add_f32_dpp v3, v2, v2 row_ror:4 row_mask:0xf bank_mask:0xf
	s_nop 1
	v_add_f32_dpp v2, v3, v3 row_ror:8 row_mask:0xf bank_mask:0xf
	s_nop 1
	v_readlane_b32 s100, v2, 0
	v_readlane_b32 s101, v2, 16
	v_readlane_b32 vcc_lo, v2, 32
	v_readlane_b32 vcc_hi, v2, 48
	v_mov_b32_e32 v3, s100
	v_add_f32_e32 v3, s101, v3
	v_add_f32_e32 v3, vcc_lo, v3
	v_add_f32_e32 v3, vcc_hi, v3
	v_fmamk_f32 v2, v3, 0x3a000000, v28
	v_mul_f32_e32 v3, 0x4b800000, v2
	v_cmp_gt_f32_e32 vcc, 0x800000, v2
	s_nop 1
	v_cndmask_b32_e32 v2, v2, v3, vcc
	v_rsq_f32_e32 v2, v2
	s_nop 0
	v_mul_f32_e32 v3, 0x45800000, v2
	v_cndmask_b32_e32 v2, v2, v3, vcc
	v_pk_mul_f32 v[64:65], v[64:65], v[2:3] op_sel_hi:[1,0]
	v_pk_mul_f32 v[66:67], v[66:67], v[2:3] op_sel_hi:[1,0]
	v_pk_mul_f32 v[64:65], v[64:65], v[96:97]
	v_pk_mul_f32 v[66:67], v[66:67], v[98:99]
	v_cvt_pk_bf16_f32 v6, v64, v65
	v_cvt_pk_bf16_f32 v7, v66, v67
	global_store_dwordx2 v1, v[6:7], s[10:11]
	v_pk_mul_f32 v[68:69], v[68:69], v[2:3] op_sel_hi:[1,0]
	v_pk_mul_f32 v[70:71], v[70:71], v[2:3] op_sel_hi:[1,0]
	v_pk_mul_f32 v[68:69], v[68:69], v[100:101]
	v_pk_mul_f32 v[70:71], v[70:71], v[102:103]
	v_cvt_pk_bf16_f32 v8, v68, v69
	v_cvt_pk_bf16_f32 v9, v70, v71
	global_store_dwordx2 v1, v[8:9], s[10:11] offset:512
	v_pk_mul_f32 v[72:73], v[72:73], v[2:3] op_sel_hi:[1,0]
	v_pk_mul_f32 v[74:75], v[74:75], v[2:3] op_sel_hi:[1,0]
	v_pk_mul_f32 v[72:73], v[72:73], v[104:105]
	v_pk_mul_f32 v[74:75], v[74:75], v[106:107]
	v_cvt_pk_bf16_f32 v6, v72, v73
	v_cvt_pk_bf16_f32 v7, v74, v75
	global_store_dwordx2 v1, v[6:7], s[10:11] offset:1024
	v_pk_mul_f32 v[76:77], v[76:77], v[2:3] op_sel_hi:[1,0]
	v_pk_mul_f32 v[78:79], v[78:79], v[2:3] op_sel_hi:[1,0]
	v_pk_mul_f32 v[76:77], v[76:77], v[108:109]
	v_pk_mul_f32 v[78:79], v[78:79], v[110:111]
	v_cvt_pk_bf16_f32 v8, v76, v77
	v_cvt_pk_bf16_f32 v9, v78, v79
	global_store_dwordx2 v1, v[8:9], s[10:11] offset:1536
	v_pk_mul_f32 v[80:81], v[80:81], v[2:3] op_sel_hi:[1,0]
	v_pk_mul_f32 v[82:83], v[82:83], v[2:3] op_sel_hi:[1,0]
	v_pk_mul_f32 v[80:81], v[80:81], v[112:113]
	v_pk_mul_f32 v[82:83], v[82:83], v[114:115]
	v_cvt_pk_bf16_f32 v6, v80, v81
	v_cvt_pk_bf16_f32 v7, v82, v83
	global_store_dwordx2 v1, v[6:7], s[10:11] offset:2048
	v_pk_mul_f32 v[84:85], v[84:85], v[2:3] op_sel_hi:[1,0]
	v_pk_mul_f32 v[86:87], v[86:87], v[2:3] op_sel_hi:[1,0]
	v_pk_mul_f32 v[84:85], v[84:85], v[116:117]
	v_pk_mul_f32 v[86:87], v[86:87], v[118:119]
	v_cvt_pk_bf16_f32 v8, v84, v85
	v_cvt_pk_bf16_f32 v9, v86, v87
	global_store_dwordx2 v1, v[8:9], s[10:11] offset:2560
	v_pk_mul_f32 v[88:89], v[88:89], v[2:3] op_sel_hi:[1,0]
	v_pk_mul_f32 v[90:91], v[90:91], v[2:3] op_sel_hi:[1,0]
	v_pk_mul_f32 v[88:89], v[88:89], v[120:121]
	v_pk_mul_f32 v[90:91], v[90:91], v[122:123]
	v_cvt_pk_bf16_f32 v6, v88, v89
	v_cvt_pk_bf16_f32 v7, v90, v91
	global_store_dwordx2 v1, v[6:7], s[10:11] offset:3072
	v_pk_mul_f32 v[92:93], v[92:93], v[2:3] op_sel_hi:[1,0]
	v_pk_mul_f32 v[94:95], v[94:95], v[2:3] op_sel_hi:[1,0]
	v_pk_mul_f32 v[92:93], v[92:93], v[124:125]
	v_pk_mul_f32 v[94:95], v[94:95], v[126:127]
	v_cvt_pk_bf16_f32 v8, v92, v93
	v_cvt_pk_bf16_f32 v9, v94, v95
	global_store_dwordx2 v1, v[8:9], s[10:11] offset:3584
	s_add_u32 s10, s10, s5
	s_addc_u32 s11, s11, 0
	s_mov_b32 s3, 1
	s_cmp_eq_u32 s0, 0
	s_cbranch_scc1 .LBB0_94
	s_branch .Lp0r_loop

.LBB0_625:
	s_cmp_lt_i32 s30, 6
	s_cselect_b64 s[0:1], -1, 0
	s_and_b64 s[4:5], s[0:1], s[4:5]
	s_andn2_b64 vcc, exec, s[4:5]
	s_cbranch_vccnz .LBB0_629
	s_lshl_b32 s0, s2, 3
	s_add_i32 s6, s33, s0
	s_cmpk_gt_i32 s6, 0x3fff
	s_cbranch_scc1 .LBB0_629
	s_waitcnt lgkmcnt(0)
	v_lshlrev_b32_e32 v0, 4, v204
	v_lshlrev_b32_e32 v1, 3, v204
	v_mov_b32_e32 v28, 0x358637bd
	s_add_u32 s0, s24, 0x1000
	s_addc_u32 s1, s25, 0
	global_load_dwordx4 v[96:99], v0, s[0:1] offset:-4096
	global_load_dwordx4 v[100:103], v0, s[0:1] offset:-3072
	global_load_dwordx4 v[104:107], v0, s[0:1] offset:-2048
	global_load_dwordx4 v[108:111], v0, s[0:1] offset:-1024
	global_load_dwordx4 v[112:115], v0, s[0:1] offset:0
	global_load_dwordx4 v[116:119], v0, s[0:1] offset:1024
	global_load_dwordx4 v[120:123], v0, s[0:1] offset:2048
	global_load_dwordx4 v[124:127], v0, s[0:1] offset:3072
	s_lshl_b32 s3, s6, 13
	s_add_u32 s8, s28, s3
	s_addc_u32 s9, s29, 0
	s_add_u32 s8, s8, 0xa201000
	s_addc_u32 s9, s9, 0
	s_lshl_b32 s3, s6, 12
	s_add_u32 s12, s28, s3
	s_addc_u32 s13, s29, 0
	s_add_u32 s12, s12, 0x6200000
	s_addc_u32 s13, s13, 0
	s_lshl_b32 s7, s34, 3
	s_lshl_b32 s14, s7, 13
	s_lshl_b32 s15, s7, 12
	global_load_dwordx4 v[32:35], v0, s[8:9] offset:-4096
	global_load_dwordx4 v[36:39], v0, s[8:9] offset:-3072
	global_load_dwordx4 v[40:43], v0, s[8:9] offset:-2048
	global_load_dwordx4 v[44:47], v0, s[8:9] offset:-1024
	global_load_dwordx4 v[48:51], v0, s[8:9] offset:0
	global_load_dwordx4 v[52:55], v0, s[8:9] offset:1024
	global_load_dwordx4 v[56:59], v0, s[8:9] offset:2048
	global_load_dwordx4 v[60:63], v0, s[8:9] offset:3072
	s_mov_b32 s3, 0
.Lp5r_loop:
	s_add_i32 s6, s6, s7
	s_cmp_lt_i32 s6, 0x4000
	s_cselect_b32 s0, 1, 0
	s_cbranch_scc0 .Lp5r_a_nonext
	s_add_u32 s8, s8, s14
	s_addc_u32 s9, s9, 0
	global_load_dwordx4 v[64:67], v0, s[8:9] offset:-4096
	global_load_dwordx4 v[68:71], v0, s[8:9] offset:-3072
	global_load_dwordx4 v[72:75], v0, s[8:9] offset:-2048
	global_load_dwordx4 v[76:79], v0, s[8:9] offset:-1024
	global_load_dwordx4 v[80:83], v0, s[8:9] offset:0
	global_load_dwordx4 v[84:87], v0, s[8:9] offset:1024
	global_load_dwordx4 v[88:91], v0, s[8:9] offset:2048
	global_load_dwordx4 v[92:95], v0, s[8:9] offset:3072

.Lp5r_a_go:
	v_pk_mul_f32 v[2:3], v[32:33], v[32:33]
	v_pk_mul_f32 v[4:5], v[34:35], v[34:35]
	v_pk_fma_f32 v[2:3], v[36:37], v[36:37], v[2:3]
	v_pk_fma_f32 v[4:5], v[38:39], v[38:39], v[4:5]
	v_pk_fma_f32 v[2:3], v[40:41], v[40:41], v[2:3]
	v_pk_fma_f32 v[4:5], v[42:43], v[42:43], v[4:5]
	v_pk_fma_f32 v[2:3], v[44:45], v[44:45], v[2:3]
	v_pk_fma_f32 v[4:5], v[46:47], v[46:47], v[4:5]
	v_pk_fma_f32 v[2:3], v[48:49], v[48:49], v[2:3]
	v_pk_fma_f32 v[4:5], v[50:51], v[50:51], v[4:5]
	v_pk_fma_f32 v[2:3], v[52:53], v[52:53], v[2:3]
	v_pk_fma_f32 v[4:5], v[54:55], v[54:55], v[4:5]
	v_pk_fma_f32 v[2:3], v[56:57], v[56:57], v[2:3]
	v_pk_fma_f32 v[4:5], v[58:59], v[58:59], v[4:5]
	v_pk_fma_f32 v[2:3], v[60:61], v[60:61], v[2:3]
	v_pk_fma_f32 v[4:5], v[62:63], v[62:63], v[4:5]
	v_pk_add_f32 v[2:3], v[2:3], v[4:5]
	s_nop 0
	v_add_f32_e32 v2, v2, v3
	s_nop 1
	v_add_f32_dpp v3, v2, v2 quad_perm:[1,0,3,2] row_mask:0xf bank_mask:0xf
	s_nop 1
	v_add_f32_dpp v2, v3, v3 quad_perm:[2,3,0,1] row_mask:0xf bank_mask:0xf
	s_nop 1
	v_add_f32_dpp v3, v2, v2 row_ror:4 row_mask:0xf bank_mask:0xf
	s_nop 1
	v_add_f32_dpp v2, v3, v3 row_ror:8 row_mask:0xf bank_mask:0xf
	s_nop 1
	v_readlane_b32 s100, v2, 0
	v_readlane_b32 s101, v2, 16
	v_readlane_b32 vcc_lo, v2, 32
	v_readlane_b32 vcc_hi, v2, 48
	v_mov_b32_e32 v3, s100
	v_add_f32_e32 v3, s101, v3
	v_add_f32_e32 v3, vcc_lo, v3
	v_add_f32_e32 v3, vcc_hi, v3
	v_fmamk_f32 v2, v3, 0x3a000000, v28
	v_mul_f32_e32 v3, 0x4b800000, v2
	v_cmp_gt_f32_e32 vcc, 0x800000, v2
	s_nop 1
	v_cndmask_b32_e32 v2, v2, v3, vcc
	v_rsq_f32_e32 v2, v2
	s_nop 0
	v_mul_f32_e32 v3, 0x45800000, v2
	v_cndmask_b32_e32 v2, v2, v3, vcc
	v_pk_mul_f32 v[32:33], v[32:33], v[2:3] op_sel_hi:[1,0]
	v_pk_mul_f32 v[34:35], v[34:35], v[2:3] op_sel_hi:[1,0]
	v_pk_mul_f32 v[32:33], v[32:33], v[96:97]
	v_pk_mul_f32 v[34:35], v[34:35], v[98:99]
	v_cvt_pk_bf16_f32 v6, v32, v33
	v_cvt_pk_bf16_f32 v7, v34, v35
	global_store_dwordx2 v1, v[6:7], s[12:13]
	v_pk_mul_f32 v[36:37], v[36:37], v[2:3] op_sel_hi:[1,0]
	v_pk_mul_f32 v[38:39], v[38:39], v[2:3] op_sel_hi:[1,0]
	v_pk_mul_f32 v[36:37], v[36:37], v[100:101]
	v_pk_mul_f32 v[38:39], v[38:39], v[102:103]
	v_cvt_pk_bf16_f32 v8, v36, v37
	v_cvt_pk_bf16_f32 v9, v38, v39
	global_store_dwordx2 v1, v[8:9], s[12:13] offset:512
	v_pk_mul_f32 v[40:41], v[40:41], v[2:3] op_sel_hi:[1,0]
	v_pk_mul_f32 v[42:43], v[42:43], v[2:3] op_sel_hi:[1,0]
	v_pk_mul_f32 v[40:41], v[40:41], v[104:105]
	v_pk_mul_f32 v[42:43], v[42:43], v[106:107]
	v_cvt_pk_bf16_f32 v6, v40, v41
	v_cvt_pk_bf16_f32 v7, v42, v43
	global_store_dwordx2 v1, v[6:7], s[12:13] offset:1024
	v_pk_mul_f32 v[44:45], v[44:45], v[2:3] op_sel_hi:[1,0]
	v_pk_mul_f32 v[46:47], v[46:47], v[2:3] op_sel_hi:[1,0]
	v_pk_mul_f32 v[44:45], v[44:45], v[108:109]
	v_pk_mul_f32 v[46:47], v[46:47], v[110:111]
	v_cvt_pk_bf16_f32 v8, v44, v45
	v_cvt_pk_bf16_f32 v9, v46, v47
	global_store_dwordx2 v1, v[8:9], s[12:13] offset:1536
	v_pk_mul_f32 v[48:49], v[48:49], v[2:3] op_sel_hi:[1,0]
	v_pk_mul_f32 v[50:51], v[50:51], v[2:3] op_sel_hi:[1,0]
	v_pk_mul_f32 v[48:49], v[48:49], v[112:113]
	v_pk_mul_f32 v[50:51], v[50:51], v[114:115]
	v_cvt_pk_bf16_f32 v6, v48, v49
	v_cvt_pk_bf16_f32 v7, v50, v51
	global_store_dwordx2 v1, v[6:7], s[12:13] offset:2048
	v_pk_mul_f32 v[52:53], v[52:53], v[2:3] op_sel_hi:[1,0]
	v_pk_mul_f32 v[54:55], v[54:55], v[2:3] op_sel_hi:[1,0]
	v_pk_mul_f32 v[52:53], v[52:53], v[116:117]
	v_pk_mul_f32 v[54:55], v[54:55], v[118:119]
	v_cvt_pk_bf16_f32 v8, v52, v53
	v_cvt_pk_bf16_f32 v9, v54, v55
	global_store_dwordx2 v1, v[8:9], s[12:13] offset:2560
	v_pk_mul_f32 v[56:57], v[56:57], v[2:3] op_sel_hi:[1,0]
	v_pk_mul_f32 v[58:59], v[58:59], v[2:3] op_sel_hi:[1,0]
	v_pk_mul_f32 v[56:57], v[56:57], v[120:121]
	v_pk_mul_f32 v[58:59], v[58:59], v[122:123]
	v_cvt_pk_bf16_f32 v6, v56, v57
	v_cvt_pk_bf16_f32 v7, v58, v59
	global_store_dwordx2 v1, v[6:7], s[12:13] offset:3072
	v_pk_mul_f32 v[60:61], v[60:61], v[2:3] op_sel_hi:[1,0]
	v_pk_mul_f32 v[62:63], v[62:63], v[2:3] op_sel_hi:[1,0]
	v_pk_mul_f32 v[60:61], v[60:61], v[124:125]
	v_pk_mul_f32 v[62:63], v[62:63], v[126:127]
	v_cvt_pk_bf16_f32 v8, v60, v61
	v_cvt_pk_bf16_f32 v9, v62, v63
	global_store_dwordx2 v1, v[8:9], s[12:13] offset:3584
	s_add_u32 s12, s12, s15
	s_addc_u32 s13, s13, 0
	s_mov_b32 s3, 1
	s_cmp_eq_u32 s0, 0
	s_cbranch_scc1 .LBB0_629
	s_add_i32 s6, s6, s7
	s_cmp_lt_i32 s6, 0x4000
	s_cselect_b32 s0, 1, 0
	s_cbranch_scc0 .Lp5r_b_nonext
	s_add_u32 s8, s8, s14
	s_addc_u32 s9, s9, 0
	global_load_dwordx4 v[32:35], v0, s[8:9] offset:-4096
	global_load_dwordx4 v[36:39], v0, s[8:9] offset:-3072
	global_load_dwordx4 v[40:43], v0, s[8:9] offset:-2048
	global_load_dwordx4 v[44:47], v0, s[8:9] offset:-1024
	global_load_dwordx4 v[48:51], v0, s[8:9] offset:0
	global_load_dwordx4 v[52:55], v0, s[8:9] offset:1024
	global_load_dwordx4 v[56:59], v0, s[8:9] offset:2048
	global_load_dwordx4 v[60:63], v0, s[8:9] offset:3072

.Lp5r_b_go:
	v_pk_mul_f32 v[2:3], v[64:65], v[64:65]
	v_pk_mul_f32 v[4:5], v[66:67], v[66:67]
	v_pk_fma_f32 v[2:3], v[68:69], v[68:69], v[2:3]
	v_pk_fma_f32 v[4:5], v[70:71], v[70:71], v[4:5]
	v_pk_fma_f32 v[2:3], v[72:73], v[72:73], v[2:3]
	v_pk_fma_f32 v[4:5], v[74:75], v[74:75], v[4:5]
	v_pk_fma_f32 v[2:3], v[76:77], v[76:77], v[2:3]
	v_pk_fma_f32 v[4:5], v[78:79], v[78:79], v[4:5]
	v_pk_fma_f32 v[2:3], v[80:81], v[80:81], v[2:3]
	v_pk_fma_f32 v[4:5], v[82:83], v[82:83], v[4:5]
	v_pk_fma_f32 v[2:3], v[84:85], v[84:85], v[2:3]
	v_pk_fma_f32 v[4:5], v[86:87], v[86:87], v[4:5]
	v_pk_fma_f32 v[2:3], v[88:89], v[88:89], v[2:3]
	v_pk_fma_f32 v[4:5], v[90:91], v[90:91], v[4:5]
	v_pk_fma_f32 v[2:3], v[92:93], v[92:93], v[2:3]
	v_pk_fma_f32 v[4:5], v[94:95], v[94:95], v[4:5]
	v_pk_add_f32 v[2:3], v[2:3], v[4:5]
	s_nop 0
	v_add_f32_e32 v2, v2, v3
	s_nop 1
	v_add_f32_dpp v3, v2, v2 quad_perm:[1,0,3,2] row_mask:0xf bank_mask:0xf
	s_nop 1
	v_add_f32_dpp v2, v3, v3 quad_perm:[2,3,0,1] row_mask:0xf bank_mask:0xf
	s_nop 1
	v_add_f32_dpp v3, v2, v2 row_ror:4 row_mask:0xf bank_mask:0xf
	s_nop 1
	v_add_f32_dpp v2, v3, v3 row_ror:8 row_mask:0xf bank_mask:0xf
	s_nop 1
	v_readlane_b32 s100, v2, 0
	v_readlane_b32 s101, v2, 16
	v_readlane_b32 vcc_lo, v2, 32
	v_readlane_b32 vcc_hi, v2, 48
	v_mov_b32_e32 v3, s100
	v_add_f32_e32 v3, s101, v3
	v_add_f32_e32 v3, vcc_lo, v3
	v_add_f32_e32 v3, vcc_hi, v3
	v_fmamk_f32 v2, v3, 0x3a000000, v28
	v_mul_f32_e32 v3, 0x4b800000, v2
	v_cmp_gt_f32_e32 vcc, 0x800000, v2
	s_nop 1
	v_cndmask_b32_e32 v2, v2, v3, vcc
	v_rsq_f32_e32 v2, v2
	s_nop 0
	v_mul_f32_e32 v3, 0x45800000, v2
	v_cndmask_b32_e32 v2, v2, v3, vcc
	v_pk_mul_f32 v[64:65], v[64:65], v[2:3] op_sel_hi:[1,0]
	v_pk_mul_f32 v[66:67], v[66:67], v[2:3] op_sel_hi:[1,0]
	v_pk_mul_f32 v[64:65], v[64:65], v[96:97]
	v_pk_mul_f32 v[66:67], v[66:67], v[98:99]
	v_cvt_pk_bf16_f32 v6, v64, v65
	v_cvt_pk_bf16_f32 v7, v66, v67
	global_store_dwordx2 v1, v[6:7], s[12:13]
	v_pk_mul_f32 v[68:69], v[68:69], v[2:3] op_sel_hi:[1,0]
	v_pk_mul_f32 v[70:71], v[70:71], v[2:3] op_sel_hi:[1,0]
	v_pk_mul_f32 v[68:69], v[68:69], v[100:101]
	v_pk_mul_f32 v[70:71], v[70:71], v[102:103]
	v_cvt_pk_bf16_f32 v8, v68, v69
	v_cvt_pk_bf16_f32 v9, v70, v71
	global_store_dwordx2 v1, v[8:9], s[12:13] offset:512
	v_pk_mul_f32 v[72:73], v[72:73], v[2:3] op_sel_hi:[1,0]
	v_pk_mul_f32 v[74:75], v[74:75], v[2:3] op_sel_hi:[1,0]
	v_pk_mul_f32 v[72:73], v[72:73], v[104:105]
	v_pk_mul_f32 v[74:75], v[74:75], v[106:107]
	v_cvt_pk_bf16_f32 v6, v72, v73
	v_cvt_pk_bf16_f32 v7, v74, v75
	global_store_dwordx2 v1, v[6:7], s[12:13] offset:1024
	v_pk_mul_f32 v[76:77], v[76:77], v[2:3] op_sel_hi:[1,0]
	v_pk_mul_f32 v[78:79], v[78:79], v[2:3] op_sel_hi:[1,0]
	v_pk_mul_f32 v[76:77], v[76:77], v[108:109]
	v_pk_mul_f32 v[78:79], v[78:79], v[110:111]
	v_cvt_pk_bf16_f32 v8, v76, v77
	v_cvt_pk_bf16_f32 v9, v78, v79
	global_store_dwordx2 v1, v[8:9], s[12:13] offset:1536
	v_pk_mul_f32 v[80:81], v[80:81], v[2:3] op_sel_hi:[1,0]
	v_pk_mul_f32 v[82:83], v[82:83], v[2:3] op_sel_hi:[1,0]
	v_pk_mul_f32 v[80:81], v[80:81], v[112:113]
	v_pk_mul_f32 v[82:83], v[82:83], v[114:115]
	v_cvt_pk_bf16_f32 v6, v80, v81
	v_cvt_pk_bf16_f32 v7, v82, v83
	global_store_dwordx2 v1, v[6:7], s[12:13] offset:2048
	v_pk_mul_f32 v[84:85], v[84:85], v[2:3] op_sel_hi:[1,0]
	v_pk_mul_f32 v[86:87], v[86:87], v[2:3] op_sel_hi:[1,0]
	v_pk_mul_f32 v[84:85], v[84:85], v[116:117]
	v_pk_mul_f32 v[86:87], v[86:87], v[118:119]
	v_cvt_pk_bf16_f32 v8, v84, v85
	v_cvt_pk_bf16_f32 v9, v86, v87
	global_store_dwordx2 v1, v[8:9], s[12:13] offset:2560
	v_pk_mul_f32 v[88:89], v[88:89], v[2:3] op_sel_hi:[1,0]
	v_pk_mul_f32 v[90:91], v[90:91], v[2:3] op_sel_hi:[1,0]
	v_pk_mul_f32 v[88:89], v[88:89], v[120:121]
	v_pk_mul_f32 v[90:91], v[90:91], v[122:123]
	v_cvt_pk_bf16_f32 v6, v88, v89
	v_cvt_pk_bf16_f32 v7, v90, v91
	global_store_dwordx2 v1, v[6:7], s[12:13] offset:3072
	v_pk_mul_f32 v[92:93], v[92:93], v[2:3] op_sel_hi:[1,0]
	v_pk_mul_f32 v[94:95], v[94:95], v[2:3] op_sel_hi:[1,0]
	v_pk_mul_f32 v[92:93], v[92:93], v[124:125]
	v_pk_mul_f32 v[94:95], v[94:95], v[126:127]
	v_cvt_pk_bf16_f32 v8, v92, v93
	v_cvt_pk_bf16_f32 v9, v94, v95
	global_store_dwordx2 v1, v[8:9], s[12:13] offset:3584
	s_add_u32 s12, s12, s15
	s_addc_u32 s13, s13, 0
	s_mov_b32 s3, 1
	s_cmp_eq_u32 s0, 0
	s_cbranch_scc1 .LBB0_629
	s_branch .Lp5r_loop

.LBB0_837:
	s_cmp_lt_i32 s30, 9
	s_cselect_b64 s[4:5], -1, 0
	s_and_b64 s[0:1], s[4:5], s[0:1]
	s_andn2_b64 vcc, exec, s[0:1]
	s_cbranch_vccnz .LBB0_841
	s_lshl_b32 s0, s2, 3
	s_add_i32 s0, s33, s0
	s_cmpk_gt_i32 s0, 0x3fff
	s_cbranch_scc1 .LBB0_841
	s_mov_b32 s6, s0
	s_waitcnt lgkmcnt(0)
	v_lshlrev_b32_e32 v0, 4, v204
	v_mov_b32_e32 v28, 0x358637bd
	s_add_u32 s0, s56, 0x1000
	s_addc_u32 s1, s57, 0
	global_load_dwordx4 v[96:99], v0, s[0:1] offset:-4096
	global_load_dwordx4 v[100:103], v0, s[0:1] offset:-3072
	global_load_dwordx4 v[104:107], v0, s[0:1] offset:-2048
	global_load_dwordx4 v[108:111], v0, s[0:1] offset:-1024
	global_load_dwordx4 v[112:115], v0, s[0:1] offset:0
	global_load_dwordx4 v[116:119], v0, s[0:1] offset:1024
	global_load_dwordx4 v[120:123], v0, s[0:1] offset:2048
	global_load_dwordx4 v[124:127], v0, s[0:1] offset:3072
	s_lshl_b32 s3, s6, 13
	s_add_u32 s8, s58, s3
	s_addc_u32 s9, s59, 0
	s_add_u32 s8, s8, 0x1000
	s_addc_u32 s9, s9, 0
	s_mov_b64 s[12:13], s[8:9]
	s_lshl_b32 s7, s34, 3
	s_lshl_b32 s14, s7, 13
	global_load_dwordx4 v[32:35], v0, s[8:9] offset:-4096
	global_load_dwordx4 v[36:39], v0, s[8:9] offset:-3072
	global_load_dwordx4 v[40:43], v0, s[8:9] offset:-2048
	global_load_dwordx4 v[44:47], v0, s[8:9] offset:-1024
	global_load_dwordx4 v[48:51], v0, s[8:9] offset:0
	global_load_dwordx4 v[52:55], v0, s[8:9] offset:1024
	global_load_dwordx4 v[56:59], v0, s[8:9] offset:2048
	global_load_dwordx4 v[60:63], v0, s[8:9] offset:3072
	s_mov_b32 s3, 0

.Lp8r_a_go:
	v_pk_mul_f32 v[2:3], v[32:33], v[32:33]
	v_pk_mul_f32 v[4:5], v[34:35], v[34:35]
	v_pk_fma_f32 v[2:3], v[36:37], v[36:37], v[2:3]
	v_pk_fma_f32 v[4:5], v[38:39], v[38:39], v[4:5]
	v_pk_fma_f32 v[2:3], v[40:41], v[40:41], v[2:3]
	v_pk_fma_f32 v[4:5], v[42:43], v[42:43], v[4:5]
	v_pk_fma_f32 v[2:3], v[44:45], v[44:45], v[2:3]
	v_pk_fma_f32 v[4:5], v[46:47], v[46:47], v[4:5]
	v_pk_fma_f32 v[2:3], v[48:49], v[48:49], v[2:3]
	v_pk_fma_f32 v[4:5], v[50:51], v[50:51], v[4:5]
	v_pk_fma_f32 v[2:3], v[52:53], v[52:53], v[2:3]
	v_pk_fma_f32 v[4:5], v[54:55], v[54:55], v[4:5]
	v_pk_fma_f32 v[2:3], v[56:57], v[56:57], v[2:3]
	v_pk_fma_f32 v[4:5], v[58:59], v[58:59], v[4:5]
	v_pk_fma_f32 v[2:3], v[60:61], v[60:61], v[2:3]
	v_pk_fma_f32 v[4:5], v[62:63], v[62:63], v[4:5]
	v_pk_add_f32 v[2:3], v[2:3], v[4:5]
	s_nop 0
	v_add_f32_e32 v2, v2, v3
	s_nop 1
	v_add_f32_dpp v3, v2, v2 quad_perm:[1,0,3,2] row_mask:0xf bank_mask:0xf
	s_nop 1
	v_add_f32_dpp v2, v3, v3 quad_perm:[2,3,0,1] row_mask:0xf bank_mask:0xf
	s_nop 1
	v_add_f32_dpp v3, v2, v2 row_ror:4 row_mask:0xf bank_mask:0xf
	s_nop 1
	v_add_f32_dpp v2, v3, v3 row_ror:8 row_mask:0xf bank_mask:0xf
	s_nop 1
	v_readlane_b32 s100, v2, 0
	v_readlane_b32 s101, v2, 16
	v_readlane_b32 vcc_lo, v2, 32
	v_readlane_b32 vcc_hi, v2, 48
	v_mov_b32_e32 v3, s100
	v_add_f32_e32 v3, s101, v3
	v_add_f32_e32 v3, vcc_lo, v3
	v_add_f32_e32 v3, vcc_hi, v3
	v_fmamk_f32 v2, v3, 0x3a000000, v28
	v_mul_f32_e32 v3, 0x4b800000, v2
	v_cmp_gt_f32_e32 vcc, 0x800000, v2
	s_nop 1
	v_cndmask_b32_e32 v2, v2, v3, vcc
	v_rsq_f32_e32 v2, v2
	s_nop 0
	v_mul_f32_e32 v3, 0x45800000, v2
	v_cndmask_b32_e32 v2, v2, v3, vcc
	v_pk_mul_f32 v[32:33], v[32:33], v[2:3] op_sel_hi:[1,0]
	v_pk_mul_f32 v[34:35], v[34:35], v[2:3] op_sel_hi:[1,0]
	v_pk_mul_f32 v[32:33], v[32:33], v[96:97]
	v_pk_mul_f32 v[34:35], v[34:35], v[98:99]
	global_store_dwordx4 v0, v[32:35], s[12:13] offset:-4096
	v_pk_mul_f32 v[36:37], v[36:37], v[2:3] op_sel_hi:[1,0]
	v_pk_mul_f32 v[38:39], v[38:39], v[2:3] op_sel_hi:[1,0]
	v_pk_mul_f32 v[36:37], v[36:37], v[100:101]
	v_pk_mul_f32 v[38:39], v[38:39], v[102:103]
	global_store_dwordx4 v0, v[36:39], s[12:13] offset:-3072
	v_pk_mul_f32 v[40:41], v[40:41], v[2:3] op_sel_hi:[1,0]
	v_pk_mul_f32 v[42:43], v[42:43], v[2:3] op_sel_hi:[1,0]
	v_pk_mul_f32 v[40:41], v[40:41], v[104:105]
	v_pk_mul_f32 v[42:43], v[42:43], v[106:107]
	global_store_dwordx4 v0, v[40:43], s[12:13] offset:-2048
	v_pk_mul_f32 v[44:45], v[44:45], v[2:3] op_sel_hi:[1,0]
	v_pk_mul_f32 v[46:47], v[46:47], v[2:3] op_sel_hi:[1,0]
	v_pk_mul_f32 v[44:45], v[44:45], v[108:109]
	v_pk_mul_f32 v[46:47], v[46:47], v[110:111]
	global_store_dwordx4 v0, v[44:47], s[12:13] offset:-1024
	v_pk_mul_f32 v[48:49], v[48:49], v[2:3] op_sel_hi:[1,0]
	v_pk_mul_f32 v[50:51], v[50:51], v[2:3] op_sel_hi:[1,0]
	v_pk_mul_f32 v[48:49], v[48:49], v[112:113]
	v_pk_mul_f32 v[50:51], v[50:51], v[114:115]
	global_store_dwordx4 v0, v[48:51], s[12:13] offset:0
	v_pk_mul_f32 v[52:53], v[52:53], v[2:3] op_sel_hi:[1,0]
	v_pk_mul_f32 v[54:55], v[54:55], v[2:3] op_sel_hi:[1,0]
	v_pk_mul_f32 v[52:53], v[52:53], v[116:117]
	v_pk_mul_f32 v[54:55], v[54:55], v[118:119]
	global_store_dwordx4 v0, v[52:55], s[12:13] offset:1024
	v_pk_mul_f32 v[56:57], v[56:57], v[2:3] op_sel_hi:[1,0]
	v_pk_mul_f32 v[58:59], v[58:59], v[2:3] op_sel_hi:[1,0]
	v_pk_mul_f32 v[56:57], v[56:57], v[120:121]
	v_pk_mul_f32 v[58:59], v[58:59], v[122:123]
	global_store_dwordx4 v0, v[56:59], s[12:13] offset:2048
	v_pk_mul_f32 v[60:61], v[60:61], v[2:3] op_sel_hi:[1,0]
	v_pk_mul_f32 v[62:63], v[62:63], v[2:3] op_sel_hi:[1,0]
	v_pk_mul_f32 v[60:61], v[60:61], v[124:125]
	v_pk_mul_f32 v[62:63], v[62:63], v[126:127]
	global_store_dwordx4 v0, v[60:63], s[12:13] offset:3072
	s_mov_b64 s[12:13], s[8:9]
	s_mov_b32 s3, 1
	s_cmp_eq_u32 s0, 0
	s_cbranch_scc1 .LBB0_841
	s_add_i32 s6, s6, s7
	s_cmp_lt_i32 s6, 0x4000
	s_cselect_b32 s0, 1, 0
	s_cbranch_scc0 .Lp8r_b_nonext
	s_add_u32 s8, s8, s14
	s_addc_u32 s9, s9, 0
	global_load_dwordx4 v[32:35], v0, s[8:9] offset:-4096
	global_load_dwordx4 v[36:39], v0, s[8:9] offset:-3072
	global_load_dwordx4 v[40:43], v0, s[8:9] offset:-2048
	global_load_dwordx4 v[44:47], v0, s[8:9] offset:-1024
	global_load_dwordx4 v[48:51], v0, s[8:9] offset:0
	global_load_dwordx4 v[52:55], v0, s[8:9] offset:1024
	global_load_dwordx4 v[56:59], v0, s[8:9] offset:2048
	global_load_dwordx4 v[60:63], v0, s[8:9] offset:3072

.Lp8r_b_go:
	v_pk_mul_f32 v[2:3], v[64:65], v[64:65]
	v_pk_mul_f32 v[4:5], v[66:67], v[66:67]
	v_pk_fma_f32 v[2:3], v[68:69], v[68:69], v[2:3]
	v_pk_fma_f32 v[4:5], v[70:71], v[70:71], v[4:5]
	v_pk_fma_f32 v[2:3], v[72:73], v[72:73], v[2:3]
	v_pk_fma_f32 v[4:5], v[74:75], v[74:75], v[4:5]
	v_pk_fma_f32 v[2:3], v[76:77], v[76:77], v[2:3]
	v_pk_fma_f32 v[4:5], v[78:79], v[78:79], v[4:5]
	v_pk_fma_f32 v[2:3], v[80:81], v[80:81], v[2:3]
	v_pk_fma_f32 v[4:5], v[82:83], v[82:83], v[4:5]
	v_pk_fma_f32 v[2:3], v[84:85], v[84:85], v[2:3]
	v_pk_fma_f32 v[4:5], v[86:87], v[86:87], v[4:5]
	v_pk_fma_f32 v[2:3], v[88:89], v[88:89], v[2:3]
	v_pk_fma_f32 v[4:5], v[90:91], v[90:91], v[4:5]
	v_pk_fma_f32 v[2:3], v[92:93], v[92:93], v[2:3]
	v_pk_fma_f32 v[4:5], v[94:95], v[94:95], v[4:5]
	v_pk_add_f32 v[2:3], v[2:3], v[4:5]
	s_nop 0
	v_add_f32_e32 v2, v2, v3
	s_nop 1
	v_add_f32_dpp v3, v2, v2 quad_perm:[1,0,3,2] row_mask:0xf bank_mask:0xf
	s_nop 1
	v_add_f32_dpp v2, v3, v3 quad_perm:[2,3,0,1] row_mask:0xf bank_mask:0xf
	s_nop 1
	v_add_f32_dpp v3, v2, v2 row_ror:4 row_mask:0xf bank_mask:0xf
	s_nop 1
	v_add_f32_dpp v2, v3, v3 row_ror:8 row_mask:0xf bank_mask:0xf
	s_nop 1
	v_readlane_b32 s100, v2, 0
	v_readlane_b32 s101, v2, 16
	v_readlane_b32 vcc_lo, v2, 32
	v_readlane_b32 vcc_hi, v2, 48
	v_mov_b32_e32 v3, s100
	v_add_f32_e32 v3, s101, v3
	v_add_f32_e32 v3, vcc_lo, v3
	v_add_f32_e32 v3, vcc_hi, v3
	v_fmamk_f32 v2, v3, 0x3a000000, v28
	v_mul_f32_e32 v3, 0x4b800000, v2
	v_cmp_gt_f32_e32 vcc, 0x800000, v2
	s_nop 1
	v_cndmask_b32_e32 v2, v2, v3, vcc
	v_rsq_f32_e32 v2, v2
	s_nop 0
	v_mul_f32_e32 v3, 0x45800000, v2
	v_cndmask_b32_e32 v2, v2, v3, vcc
	v_pk_mul_f32 v[64:65], v[64:65], v[2:3] op_sel_hi:[1,0]
	v_pk_mul_f32 v[66:67], v[66:67], v[2:3] op_sel_hi:[1,0]
	v_pk_mul_f32 v[64:65], v[64:65], v[96:97]
	v_pk_mul_f32 v[66:67], v[66:67], v[98:99]
	global_store_dwordx4 v0, v[64:67], s[12:13] offset:-4096
	v_pk_mul_f32 v[68:69], v[68:69], v[2:3] op_sel_hi:[1,0]
	v_pk_mul_f32 v[70:71], v[70:71], v[2:3] op_sel_hi:[1,0]
	v_pk_mul_f32 v[68:69], v[68:69], v[100:101]
	v_pk_mul_f32 v[70:71], v[70:71], v[102:103]
	global_store_dwordx4 v0, v[68:71], s[12:13] offset:-3072
	v_pk_mul_f32 v[72:73], v[72:73], v[2:3] op_sel_hi:[1,0]
	v_pk_mul_f32 v[74:75], v[74:75], v[2:3] op_sel_hi:[1,0]
	v_pk_mul_f32 v[72:73], v[72:73], v[104:105]
	v_pk_mul_f32 v[74:75], v[74:75], v[106:107]
	global_store_dwordx4 v0, v[72:75], s[12:13] offset:-2048
	v_pk_mul_f32 v[76:77], v[76:77], v[2:3] op_sel_hi:[1,0]
	v_pk_mul_f32 v[78:79], v[78:79], v[2:3] op_sel_hi:[1,0]
	v_pk_mul_f32 v[76:77], v[76:77], v[108:109]
	v_pk_mul_f32 v[78:79], v[78:79], v[110:111]
	global_store_dwordx4 v0, v[76:79], s[12:13] offset:-1024
	v_pk_mul_f32 v[80:81], v[80:81], v[2:3] op_sel_hi:[1,0]
	v_pk_mul_f32 v[82:83], v[82:83], v[2:3] op_sel_hi:[1,0]
	v_pk_mul_f32 v[80:81], v[80:81], v[112:113]
	v_pk_mul_f32 v[82:83], v[82:83], v[114:115]
	global_store_dwordx4 v0, v[80:83], s[12:13] offset:0
	v_pk_mul_f32 v[84:85], v[84:85], v[2:3] op_sel_hi:[1,0]
	v_pk_mul_f32 v[86:87], v[86:87], v[2:3] op_sel_hi:[1,0]
	v_pk_mul_f32 v[84:85], v[84:85], v[116:117]
	v_pk_mul_f32 v[86:87], v[86:87], v[118:119]
	global_store_dwordx4 v0, v[84:87], s[12:13] offset:1024
	v_pk_mul_f32 v[88:89], v[88:89], v[2:3] op_sel_hi:[1,0]
	v_pk_mul_f32 v[90:91], v[90:91], v[2:3] op_sel_hi:[1,0]
	v_pk_mul_f32 v[88:89], v[88:89], v[120:121]
	v_pk_mul_f32 v[90:91], v[90:91], v[122:123]
	global_store_dwordx4 v0, v[88:91], s[12:13] offset:2048
	v_pk_mul_f32 v[92:93], v[92:93], v[2:3] op_sel_hi:[1,0]
	v_pk_mul_f32 v[94:95], v[94:95], v[2:3] op_sel_hi:[1,0]
	v_pk_mul_f32 v[92:93], v[92:93], v[124:125]
	v_pk_mul_f32 v[94:95], v[94:95], v[126:127]
	global_store_dwordx4 v0, v[92:95], s[12:13] offset:3072
	s_mov_b64 s[12:13], s[8:9]
	s_mov_b32 s3, 1
	s_cmp_eq_u32 s0, 0
	s_cbranch_scc1 .LBB0_841
	s_branch .Lp8r_loop
